# one static s_setprio 1 for waves 4-7 for the whole kernel (all other s_setprio deleted)
# baseline (speedup 1.0000x reference)
_Z6mk_fwd4Args:
	s_load_dwordx8 s[84:91], s[0:1], 0x80
	s_load_dwordx4 s[44:47], s[0:1], 0xa0
	s_load_dword s66, s[0:1], 0xc0
	s_mov_b32 s33, s2
	s_add_u32 s2, s0, 0xc0
	s_addc_u32 s3, s1, 0
	v_and_b32_e32 v188, 0x3ff, v0
	s_nop 0
	v_readfirstlane_b32 s98, v188
	s_cmpk_lt_u32 s98, 0x100
	s_cbranch_scc1 .Lfa_prio_glob
	s_setprio 1
.Lfa_prio_glob:
	v_writelane_b32 v235, s2, 0
	v_cmp_gt_u32_e32 vcc, 4, v188
	s_nop 0
	v_writelane_b32 v235, s3, 1
	s_and_saveexec_b64 s[2:3], vcc
	v_lshl_add_u32 v1, v188, 2, 0
	v_add_u32_e32 v1, 0x24000, v1
	v_mov_b32_e32 v2, 0
	ds_write_b32 v1, v2
	s_or_b64 exec, exec, s[2:3]
	s_waitcnt lgkmcnt(0)
	s_add_u32 s2, s44, 0x37440000
	s_addc_u32 s3, s45, 0
	v_writelane_b32 v235, s2, 2
	s_barrier
	s_nop 0
	v_writelane_b32 v235, s3, 3
	s_getreg_b32 s2, hwreg(HW_REG_XCC_ID, 0, 4)
	s_and_b32 s2, s2, 15
	v_cmp_eq_u32_e64 s[96:97], 0, v188
	v_writelane_b32 v235, s2, 4
	s_and_saveexec_b64 s[2:3], s[96:97]
	s_cbranch_execz .LBB0_5
	s_mov_b64 s[4:5], exec
	v_mbcnt_lo_u32_b32 v1, s4, 0
	v_mbcnt_hi_u32_b32 v1, s5, v1
	v_cmp_eq_u32_e32 vcc, 0, v1
	s_and_b64 s[6:7], exec, vcc
	s_mov_b64 exec, s[6:7]
	s_cbranch_execz .LBB0_5
	v_readlane_b32 s6, v235, 4
	s_bcnt1_i32_b64 s4, s[4:5]
	s_lshl_b32 s6, s6, 8
	v_mov_b32_e32 v2, s4
	v_readlane_b32 s4, v235, 2
	v_mov_b32_e32 v1, s6
	v_readlane_b32 s5, v235, 3
	s_nop 4
	global_atomic_add v1, v2, s[4:5] offset:1024
